# blocked H + P0 x-pass: norm1 gain hoisted into registers once per wave (removes 4 dependent L2 round trips and their waits per row)
# speedup vs baseline: 1.0046x; 1.0015x over previous
; #define GAS __attribute__((address_space(1)))
; __device__ __forceinline__ unsigned pk2(float lo, float hi) { const f32x2_pk v = {lo, hi}; return __builtin_bit_cast(unsigned, __builtin_convertvector(v, bf16x2_pk)); }
; __device__ __forceinline__ void rms_row_to_bf16(Frame& F, const f32x4 (&v)[4], bf16* orow, float* xinv_row) {
;     const GAS f32x4* gr = (const GAS f32x4*)F.g1 + 2 * F.lane;
;     float s = 0.f;
; #pragma unroll
;     for (int j = 0; j < 4; ++j) { s += (v[j].x * v[j].x + v[j].y * v[j].y) + (v[j].z * v[j].z + v[j].w * v[j].w); }
;     const float ms = wave_sum(s) * (1.f / D) + EPS, rstd = __builtin_amdgcn_rsqf(ms), rms = ms * rstd;
;     if (F.lane == 0) *xinv_row = rms;
;     GAS v4u* o16 = (GAS v4u*)orow + F.lane;
; #pragma unroll
;     for (int j = 0; j < 2; ++j) { const f32x4 ga = gr[128 * j], gb = gr[128 * j + 1]; const f32x4 ya = v[2 * j] * rstd * ga, yb = v[2 * j + 1] * rstd * gb;
;         v4u o; o.x = pk2(ya.x, ya.y); o.y = pk2(ya.z, ya.w); o.z = pk2(yb.x, yb.y); o.w = pk2(yb.z, yb.w); o16[64 * j] = o; }
; }
; __device__ __forceinline__ void p0_prologue(Frame& F) {
;     ...
;     const int gw = F.vcu * (NWAVES - P0_WW) + (F.wave - P0_WW), NGW = F.G * (NWAVES - P0_WW);
;     for (int m = gw; m < M; m += 4 * NGW) {
;         f32x4 v[4][4];
; #pragma unroll
;         for (int q = 0; q < 4; ++q) { const int mm = m + q * NGW; if (mm < M) { const float* xrow = mm < ROWS_P ? F.xp + (size_t)mm * D : F.xs + (size_t)(mm - ROWS_P) * D; const GAS f32x4* xr = (const GAS f32x4*)xrow + 2 * F.lane;
; #pragma unroll
;             for (int j = 0; j < 2; ++j) { v[q][2 * j] = __builtin_nontemporal_load(xr + 128 * j); v[q][2 * j + 1] = __builtin_nontemporal_load(xr + 128 * j + 1); } } else {
; #pragma unroll
;             for (int j = 0; j < 4; ++j) v[q][j] = (f32x4){0.f, 0.f, 0.f, 0.f}; } }
; #pragma unroll
;         for (int q = 0; q < 4; ++q) { const int mm = m + q * NGW; if (mm < M) rms_row_to_bf16(F, v[q], F.XN + (size_t)mm * D, F.xinv + mm); }
.LBB0_13:
	s_or_b64 exec, exec, s[4:5]
	s_add_u32 s78, s62, 0x900000
	s_addc_u32 s79, s63, 0
	s_add_u32 s64, s62, 0x1300000
	s_addc_u32 s65, s63, 0
	s_add_u32 s18, s62, 0x102000
	s_addc_u32 s19, s63, 0
	s_add_u32 s80, s62, 0x110000
	s_addc_u32 s81, s63, 0
	s_add_u32 s16, s62, 0x600000
	s_addc_u32 s17, s63, 0
	s_add_u32 s74, s62, 0xb00000
	s_addc_u32 s75, s63, 0
	s_add_u32 s66, s62, 0x2000000
	s_addc_u32 s67, s63, 0
	s_add_u32 s20, s62, 0x100000
	s_addc_u32 s21, s63, 0
	s_lshr_b32 s87, s88, 6
	s_cmp_gt_i32 s69, -1
	s_cselect_b64 s[0:1], -1, 0
	s_abs_i32 s33, s69
	s_cmp_lt_i32 s68, 1
	s_cselect_b64 s[4:5], -1, 0
	s_cmp_lg_u32 s69, 0
	s_cselect_b64 s[6:7], -1, 0
	s_and_b64 s[4:5], s[4:5], s[6:7]
	v_writelane_b32 v254, s0, 2
	s_andn2_b64 vcc, exec, s[4:5]
	v_and_b32_e32 v1, 63, v208
	v_writelane_b32 v254, s1, 3
	s_cbranch_vccnz .LBB0_235
	s_cmpk_gt_u32 s88, 0x7f
	s_mov_b64 s[4:5], -1
	s_cbranch_scc0 .LBB0_39
	s_mul_i32 s38, s43, 6
	s_add_i32 s0, s87, s38
	s_add_i32 s0, s0, -2
	s_cmp_gt_i32 s0, 0xbfff
	s_cbranch_scc1 .LBB0_38
	v_mbcnt_lo_u32_b32 v2, -1, 0
	v_mbcnt_hi_u32_b32 v2, -1, v2
	v_and_b32_e32 v3, 64, v2
	v_add_u32_e32 v3, 64, v3
	v_xor_b32_e32 v4, 1, v2
	v_cmp_lt_i32_e32 vcc, v4, v3
	v_mov_b32_e32 v67, 0
	v_lshlrev_b32_e32 v66, 5, v1
	v_cndmask_b32_e32 v4, v2, v4, vcc
	v_lshlrev_b32_e32 v72, 2, v4
	v_xor_b32_e32 v4, 2, v2
	v_cmp_lt_i32_e32 vcc, v4, v3
	s_mul_i32 s1, s42, 12
	s_mul_i32 s0, s42, 6
	v_cndmask_b32_e32 v4, v2, v4, vcc
	v_lshlrev_b32_e32 v73, 2, v4
	v_xor_b32_e32 v4, 4, v2
	v_cmp_lt_i32_e32 vcc, v4, v3
	v_lshl_add_u64 v[68:69], s[48:49], 0, v[66:67]
	global_load_dwordx4 v[90:93], v[68:69], off
	global_load_dwordx4 v[94:97], v[68:69], off offset:16
	global_load_dwordx4 v[98:101], v[68:69], off offset:2048
	global_load_dwordx4 v[102:105], v[68:69], off offset:2064
	v_lshlrev_b32_e32 v66, 4, v1
	v_cndmask_b32_e32 v4, v2, v4, vcc
	v_lshlrev_b32_e32 v74, 2, v4
	v_xor_b32_e32 v4, 8, v2
	v_cmp_lt_i32_e32 vcc, v4, v3
	s_add_i32 s39, s87, s1
	s_mul_i32 s1, s42, 18
	v_cndmask_b32_e32 v4, v2, v4, vcc
	v_lshlrev_b32_e32 v75, 2, v4
	v_xor_b32_e32 v4, 16, v2
	v_cmp_lt_i32_e32 vcc, v4, v3
	v_cmp_eq_u32_e64 s[4:5], 0, v1
	v_lshl_add_u64 v[70:71], s[66:67], 0, v[66:67]
	v_cndmask_b32_e32 v4, v2, v4, vcc
	v_lshlrev_b32_e32 v76, 2, v4
	v_xor_b32_e32 v4, 32, v2
	v_cmp_lt_i32_e32 vcc, v4, v3
	s_mul_i32 s40, s42, 24
	s_add_i32 s41, s87, s1
	v_cndmask_b32_e32 v2, v2, v4, vcc
	v_lshlrev_b32_e32 v77, 2, v2
	v_lshlrev_b32_e32 v2, 1, v1
	s_add_i32 s69, s87, s0
	v_lshlrev_b32_e32 v78, 4, v2
	v_mov_b32_e32 v79, 0x358637bd
	s_mov_b32 s72, s87
	s_branch .LBB0_19
.LBB0_17:
	s_or_b64 exec, exec, s[22:23]
	v_pk_mul_f32 v[14:15], v[14:15], v[18:19] op_sel_hi:[1,0]
	v_pk_mul_f32 v[16:17], v[16:17], v[18:19] op_sel_hi:[1,0]
	v_pk_mul_f32 v[10:11], v[10:11], v[18:19] op_sel_hi:[1,0]
	v_pk_mul_f32 v[12:13], v[12:13], v[18:19] op_sel_hi:[1,0]
	s_lshl_b64 s[6:7], s[6:7], 11
	v_lshl_add_u64 v[28:29], v[70:71], 0, s[6:7]
	v_pk_mul_f32 v[6:7], v[6:7], v[18:19] op_sel_hi:[1,0]
	v_pk_mul_f32 v[8:9], v[8:9], v[18:19] op_sel_hi:[1,0]
	v_pk_mul_f32 v[2:3], v[2:3], v[18:19] op_sel_hi:[1,0]
	v_pk_mul_f32 v[4:5], v[4:5], v[18:19] op_sel_hi:[1,0]
	v_pk_mul_f32 v[16:17], v[16:17], v[92:93]
	v_pk_mul_f32 v[14:15], v[14:15], v[90:91]
	v_pk_mul_f32 v[20:21], v[12:13], v[96:97]
	v_pk_mul_f32 v[12:13], v[10:11], v[94:95]
	v_cvt_pk_bf16_f32 v10, v14, v15
	v_cvt_pk_bf16_f32 v11, v16, v17
	v_cvt_pk_bf16_f32 v12, v12, v13
	v_cvt_pk_bf16_f32 v13, v20, v21
	global_store_dwordx4 v[28:29], v[10:13], off
	s_nop 0
	v_pk_mul_f32 v[8:9], v[8:9], v[100:101]
	v_pk_mul_f32 v[6:7], v[6:7], v[98:99]
	v_pk_mul_f32 v[10:11], v[4:5], v[104:105]
	v_pk_mul_f32 v[4:5], v[2:3], v[102:103]
	v_cvt_pk_bf16_f32 v2, v6, v7
	v_cvt_pk_bf16_f32 v3, v8, v9
	v_cvt_pk_bf16_f32 v4, v4, v5
	v_cvt_pk_bf16_f32 v5, v10, v11
	global_store_dwordx4 v[28:29], v[2:5], off offset:1024

; #define GAS __attribute__((address_space(1)))
; __device__ __forceinline__ unsigned pk2(float lo, float hi) { const f32x2_pk v = {lo, hi}; return __builtin_bit_cast(unsigned, __builtin_convertvector(v, bf16x2_pk)); }
; __device__ __forceinline__ void rms_row_to_bf16(Frame& F, const f32x4 (&v)[4], bf16* orow, float* xinv_row) {
;     const GAS f32x4* gr = (const GAS f32x4*)F.g1 + 2 * F.lane;
;     float s = 0.f;
; #pragma unroll
;     for (int j = 0; j < 4; ++j) { s += (v[j].x * v[j].x + v[j].y * v[j].y) + (v[j].z * v[j].z + v[j].w * v[j].w); }
;     const float ms = wave_sum(s) * (1.f / D) + EPS, rstd = __builtin_amdgcn_rsqf(ms), rms = ms * rstd;
;     if (F.lane == 0) *xinv_row = rms;
;     GAS v4u* o16 = (GAS v4u*)orow + F.lane;
; #pragma unroll
;     for (int j = 0; j < 2; ++j) { const f32x4 ga = gr[128 * j], gb = gr[128 * j + 1]; const f32x4 ya = v[2 * j] * rstd * ga, yb = v[2 * j + 1] * rstd * gb;
;         v4u o; o.x = pk2(ya.x, ya.y); o.y = pk2(ya.z, ya.w); o.z = pk2(yb.x, yb.y); o.w = pk2(yb.z, yb.w); o16[64 * j] = o; }
; }
.LBB0_27:
	s_or_b64 exec, exec, s[36:37]
	v_pk_mul_f32 v[64:65], v[64:65], v[66:67] op_sel_hi:[1,0]
	v_pk_mul_f32 v[62:63], v[62:63], v[66:67] op_sel_hi:[1,0]
	v_pk_mul_f32 v[60:61], v[60:61], v[66:67] op_sel_hi:[1,0]
	v_pk_mul_f32 v[58:59], v[58:59], v[66:67] op_sel_hi:[1,0]
	s_lshl_b64 s[34:35], s[34:35], 11
	v_lshl_add_u64 v[88:89], v[70:71], 0, s[34:35]
	v_pk_mul_f32 v[56:57], v[56:57], v[66:67] op_sel_hi:[1,0]
	v_pk_mul_f32 v[54:55], v[54:55], v[66:67] op_sel_hi:[1,0]
	v_pk_mul_f32 v[52:53], v[52:53], v[66:67] op_sel_hi:[1,0]
	v_pk_mul_f32 v[50:51], v[50:51], v[66:67] op_sel_hi:[1,0]
	s_andn2_b64 vcc, exec, s[30:31]
	v_pk_mul_f32 v[64:65], v[64:65], v[92:93]
	v_pk_mul_f32 v[62:63], v[62:63], v[90:91]
	v_pk_mul_f32 v[80:81], v[60:61], v[96:97]
	v_pk_mul_f32 v[60:61], v[58:59], v[94:95]
	v_cvt_pk_bf16_f32 v58, v62, v63
	v_cvt_pk_bf16_f32 v59, v64, v65
	v_cvt_pk_bf16_f32 v60, v60, v61
	v_cvt_pk_bf16_f32 v61, v80, v81
	global_store_dwordx4 v[88:89], v[58:61], off
	s_nop 0
	v_pk_mul_f32 v[56:57], v[56:57], v[100:101]
	v_pk_mul_f32 v[54:55], v[54:55], v[98:99]
	v_pk_mul_f32 v[58:59], v[52:53], v[104:105]
	v_pk_mul_f32 v[52:53], v[50:51], v[102:103]
	v_cvt_pk_bf16_f32 v50, v54, v55
	v_cvt_pk_bf16_f32 v51, v56, v57
	v_cvt_pk_bf16_f32 v52, v52, v53
	v_cvt_pk_bf16_f32 v53, v58, v59
	global_store_dwordx4 v[88:89], v[50:53], off offset:1024
	s_cbranch_vccnz .LBB0_32
	s_nop 0
	v_mul_f32_e32 v50, v47, v47
	v_mul_f32_e32 v51, v49, v49
	v_fmac_f32_e32 v50, v46, v46
	v_fmac_f32_e32 v51, v48, v48
	v_add_f32_e32 v50, v50, v51
	v_mul_f32_e32 v51, v43, v43
	v_mul_f32_e32 v52, v45, v45
	v_fmac_f32_e32 v51, v42, v42
	v_fmac_f32_e32 v52, v44, v44
	v_add_f32_e32 v51, v51, v52
	v_add_f32_e32 v50, v51, v50
	v_mul_f32_e32 v51, v39, v39
	v_mul_f32_e32 v52, v41, v41
	v_fmac_f32_e32 v51, v38, v38
	v_fmac_f32_e32 v52, v40, v40
	v_add_f32_e32 v51, v51, v52
	v_add_f32_e32 v50, v51, v50
	v_mul_f32_e32 v51, v31, v31
	v_mul_f32_e32 v52, v33, v33
	v_fmac_f32_e32 v51, v30, v30
	v_fmac_f32_e32 v52, v32, v32
	v_add_f32_e32 v51, v51, v52
	v_add_f32_e32 v50, v51, v50
	ds_bpermute_b32 v51, v72, v50
	s_ashr_i32 s27, s26, 31
	s_waitcnt lgkmcnt(0)
	v_add_f32_e32 v50, v50, v51
	ds_bpermute_b32 v51, v73, v50
	s_waitcnt lgkmcnt(0)
	v_add_f32_e32 v50, v50, v51
	ds_bpermute_b32 v51, v74, v50
	s_waitcnt lgkmcnt(0)
	v_add_f32_e32 v50, v50, v51
	ds_bpermute_b32 v51, v75, v50
	s_waitcnt lgkmcnt(0)
	v_add_f32_e32 v50, v50, v51
	ds_bpermute_b32 v51, v76, v50
	s_waitcnt lgkmcnt(0)
	v_add_f32_e32 v50, v50, v51
	ds_bpermute_b32 v51, v77, v50
	s_waitcnt lgkmcnt(0)
	v_add_f32_e32 v50, v50, v51
	v_fmamk_f32 v51, v50, 0x3a800000, v79
	v_rsq_f32_e32 v50, v51
	s_and_saveexec_b64 s[30:31], s[4:5]
	s_cbranch_execz .LBB0_30
	s_lshl_b64 s[34:35], s[26:27], 2
	s_add_u32 s34, s80, s34
	s_addc_u32 s35, s81, s35
	v_mul_f32_e32 v51, v51, v50
	global_store_dword v67, v51, s[34:35]
.LBB0_30:
	s_or_b64 exec, exec, s[30:31]
	v_pk_mul_f32 v[46:47], v[46:47], v[50:51] op_sel_hi:[1,0]
	v_pk_mul_f32 v[48:49], v[48:49], v[50:51] op_sel_hi:[1,0]
	v_pk_mul_f32 v[42:43], v[42:43], v[50:51] op_sel_hi:[1,0]
	v_pk_mul_f32 v[44:45], v[44:45], v[50:51] op_sel_hi:[1,0]
	s_lshl_b64 s[26:27], s[26:27], 11
	v_lshl_add_u64 v[60:61], v[70:71], 0, s[26:27]
	v_pk_mul_f32 v[38:39], v[38:39], v[50:51] op_sel_hi:[1,0]
	v_pk_mul_f32 v[40:41], v[40:41], v[50:51] op_sel_hi:[1,0]
	v_pk_mul_f32 v[30:31], v[30:31], v[50:51] op_sel_hi:[1,0]
	v_pk_mul_f32 v[32:33], v[32:33], v[50:51] op_sel_hi:[1,0]
	v_pk_mul_f32 v[48:49], v[48:49], v[92:93]
	v_pk_mul_f32 v[46:47], v[46:47], v[90:91]
	v_pk_mul_f32 v[52:53], v[44:45], v[96:97]
	v_pk_mul_f32 v[44:45], v[42:43], v[94:95]
	v_cvt_pk_bf16_f32 v42, v46, v47
	v_cvt_pk_bf16_f32 v43, v48, v49
	v_cvt_pk_bf16_f32 v44, v44, v45
	v_cvt_pk_bf16_f32 v45, v52, v53
	global_store_dwordx4 v[60:61], v[42:45], off
	s_nop 0
	v_pk_mul_f32 v[40:41], v[40:41], v[100:101]
	v_pk_mul_f32 v[38:39], v[38:39], v[98:99]
	v_pk_mul_f32 v[42:43], v[32:33], v[104:105]
	v_pk_mul_f32 v[32:33], v[30:31], v[102:103]
	v_cvt_pk_bf16_f32 v30, v38, v39
	v_cvt_pk_bf16_f32 v31, v40, v41
	v_cvt_pk_bf16_f32 v32, v32, v33
	v_cvt_pk_bf16_f32 v33, v42, v43
	global_store_dwordx4 v[60:61], v[30:33], off offset:1024
	s_andn2_b64 vcc, exec, s[28:29]
	s_cbranch_vccz .LBB0_33

; #define GAS __attribute__((address_space(1)))
; __device__ __forceinline__ unsigned pk2(float lo, float hi) { const f32x2_pk v = {lo, hi}; return __builtin_bit_cast(unsigned, __builtin_convertvector(v, bf16x2_pk)); }
; __device__ __forceinline__ void rms_row_to_bf16(Frame& F, const f32x4 (&v)[4], bf16* orow, float* xinv_row) {
;     ...
;     GAS v4u* o16 = (GAS v4u*)orow + F.lane;
; #pragma unroll
;     for (int j = 0; j < 2; ++j) { const f32x4 ga = gr[128 * j], gb = gr[128 * j + 1]; const f32x4 ya = v[2 * j] * rstd * ga, yb = v[2 * j + 1] * rstd * gb;
;         v4u o; o.x = pk2(ya.x, ya.y); o.y = pk2(ya.z, ya.w); o.z = pk2(yb.x, yb.y); o.w = pk2(yb.z, yb.w); o16[64 * j] = o; }
; }
.LBB0_35:
	s_or_b64 exec, exec, s[26:27]
	v_pk_mul_f32 v[32:33], v[34:35], v[30:31] op_sel_hi:[1,0]
	v_pk_mul_f32 v[34:35], v[36:37], v[30:31] op_sel_hi:[1,0]
	v_pk_mul_f32 v[26:27], v[26:27], v[30:31] op_sel_hi:[1,0]
	v_pk_mul_f32 v[28:29], v[28:29], v[30:31] op_sel_hi:[1,0]
	s_lshl_b64 s[22:23], s[22:23], 11
	v_lshl_add_u64 v[36:37], v[70:71], 0, s[22:23]
	v_pk_mul_f32 v[22:23], v[22:23], v[30:31] op_sel_hi:[1,0]
	v_pk_mul_f32 v[24:25], v[24:25], v[30:31] op_sel_hi:[1,0]
	v_pk_mul_f32 v[18:19], v[18:19], v[30:31] op_sel_hi:[1,0]
	v_pk_mul_f32 v[20:21], v[20:21], v[30:31] op_sel_hi:[1,0]
	v_pk_mul_f32 v[34:35], v[34:35], v[92:93]
	v_pk_mul_f32 v[32:33], v[32:33], v[90:91]
	v_pk_mul_f32 v[38:39], v[28:29], v[96:97]
	v_pk_mul_f32 v[28:29], v[26:27], v[94:95]
	v_cvt_pk_bf16_f32 v26, v32, v33
	v_cvt_pk_bf16_f32 v27, v34, v35
	v_cvt_pk_bf16_f32 v28, v28, v29
	v_cvt_pk_bf16_f32 v29, v38, v39
	global_store_dwordx4 v[36:37], v[26:29], off
	s_nop 0
	v_pk_mul_f32 v[24:25], v[24:25], v[100:101]
	v_pk_mul_f32 v[22:23], v[22:23], v[98:99]
	v_pk_mul_f32 v[26:27], v[20:21], v[104:105]
	v_pk_mul_f32 v[20:21], v[18:19], v[102:103]
	v_cvt_pk_bf16_f32 v18, v22, v23
	v_cvt_pk_bf16_f32 v19, v24, v25
	v_cvt_pk_bf16_f32 v20, v20, v21
	v_cvt_pk_bf16_f32 v21, v26, v27
	global_store_dwordx4 v[36:37], v[18:21], off offset:1024
	s_andn2_b64 vcc, exec, s[24:25]
	s_cbranch_vccnz .LBB0_18
